# phase-0 conversion offload ranges 14336/17408/20480 (7 whole item rounds in phase 0, 3/3/2 whole rounds per idle wave in the slots of phases 1/5/7) on top of v71
# baseline (speedup 1.0000x reference)
.LBB0_20:
	s_lshr_b32 s89, s77, 6
	s_load_dwordx16 s[8:23], s[0:1], 0x40
	s_cmp_lt_i32 s28, 1
	s_cselect_b64 s[0:1], -1, 0
	s_cmp_gt_i32 s29, 0
	s_cselect_b64 s[2:3], -1, 0
	s_and_b64 s[2:3], s[0:1], s[2:3]
	s_andn2_b64 vcc, exec, s[2:3]
	v_and_b32_e32 v227, 63, v226
	s_cbranch_vccnz .LBB0_42
	s_mov_b32 s96, 0
	s_mov_b32 s97, 0x3800
	s_lshl_b32 s0, s76, 3
	s_add_i32 s4, s0, s89

.Lp0call_1:
	v_writelane_b32 v251, s0, 0
	v_writelane_b32 v251, s1, 1
	v_writelane_b32 v251, s4, 2
	v_writelane_b32 v251, s5, 3
	v_writelane_b32 v251, s26, 4
	v_writelane_b32 v251, s27, 5
	v_writelane_b32 v251, s30, 6
	v_writelane_b32 v251, s31, 7
	v_writelane_b32 v251, s34, 8
	v_writelane_b32 v251, s35, 9
	v_writelane_b32 v251, s52, 10
	v_writelane_b32 v251, s53, 11
	v_writelane_b32 v251, s54, 12
	v_writelane_b32 v251, s55, 13
	v_writelane_b32 v251, s56, 14
	v_writelane_b32 v251, s57, 15
	v_writelane_b32 v251, s58, 16
	v_writelane_b32 v251, s59, 17
	v_writelane_b32 v251, s60, 18
	v_writelane_b32 v251, s61, 19
	v_writelane_b32 v251, s62, 20
	v_writelane_b32 v251, s63, 21
	v_writelane_b32 v251, s64, 22
	v_writelane_b32 v251, s65, 23
	v_writelane_b32 v251, s66, 24
	v_writelane_b32 v251, s67, 25
	v_writelane_b32 v251, s68, 26
	v_writelane_b32 v251, s69, 27
	v_writelane_b32 v251, s70, 28
	v_writelane_b32 v251, s71, 29
	v_writelane_b32 v251, s33, 30
	v_writelane_b32 v251, s40, 31
	v_writelane_b32 v251, s41, 32
	v_writelane_b32 v251, s42, 33
	v_writelane_b32 v251, s43, 34
	v_writelane_b32 v251, s89, 35
	v_writelane_b32 v251, vcc_lo, 36
	v_writelane_b32 v251, vcc_hi, 37
	s_nop 1
	v_readlane_b32 s0, v250, 0
	v_readlane_b32 s1, v250, 1
	s_nop 3
	s_sub_u32 s0, s0, 0x90
	s_subb_u32 s1, s1, 0
	s_load_dwordx4 s[40:43], s[0:1], 0x10
	s_lshr_b32 s89, s77, 6
	s_sub_i32 s4, s6, 0x80
	s_lshl_b32 s4, s4, 3
	s_add_i32 s4, s4, s89
	s_add_i32 s4, s4, 0x3800
	s_mov_b32 s33, 0x80
	s_mov_b32 s97, 0x4400
	s_mov_b32 s96, 1
	s_waitcnt vmcnt(0) lgkmcnt(0)
	s_branch .Lp0_entry

.Lp0call_2:
	v_writelane_b32 v251, s0, 0
	v_writelane_b32 v251, s1, 1
	v_writelane_b32 v251, s4, 2
	v_writelane_b32 v251, s5, 3
	v_writelane_b32 v251, s26, 4
	v_writelane_b32 v251, s27, 5
	v_writelane_b32 v251, s30, 6
	v_writelane_b32 v251, s31, 7
	v_writelane_b32 v251, s34, 8
	v_writelane_b32 v251, s35, 9
	v_writelane_b32 v251, s52, 10
	v_writelane_b32 v251, s53, 11
	v_writelane_b32 v251, s54, 12
	v_writelane_b32 v251, s55, 13
	v_writelane_b32 v251, s56, 14
	v_writelane_b32 v251, s57, 15
	v_writelane_b32 v251, s58, 16
	v_writelane_b32 v251, s59, 17
	v_writelane_b32 v251, s60, 18
	v_writelane_b32 v251, s61, 19
	v_writelane_b32 v251, s62, 20
	v_writelane_b32 v251, s63, 21
	v_writelane_b32 v251, s64, 22
	v_writelane_b32 v251, s65, 23
	v_writelane_b32 v251, s66, 24
	v_writelane_b32 v251, s67, 25
	v_writelane_b32 v251, s68, 26
	v_writelane_b32 v251, s69, 27
	v_writelane_b32 v251, s70, 28
	v_writelane_b32 v251, s71, 29
	v_writelane_b32 v251, s33, 30
	v_writelane_b32 v251, s40, 31
	v_writelane_b32 v251, s41, 32
	v_writelane_b32 v251, s42, 33
	v_writelane_b32 v251, s43, 34
	v_writelane_b32 v251, s89, 35
	v_writelane_b32 v251, vcc_lo, 36
	v_writelane_b32 v251, vcc_hi, 37
	s_nop 1
	v_readlane_b32 s0, v250, 0
	v_readlane_b32 s1, v250, 1
	s_nop 3
	s_sub_u32 s0, s0, 0x90
	s_subb_u32 s1, s1, 0
	s_load_dwordx4 s[40:43], s[0:1], 0x10
	s_lshr_b32 s89, s77, 6
	s_sub_i32 s4, s6, 0x80
	s_lshl_b32 s4, s4, 3
	s_add_i32 s4, s4, s89
	s_add_i32 s4, s4, 0x4400
	s_mov_b32 s33, 0x80
	s_mov_b32 s97, 0x5000
	s_mov_b32 s96, 2
	s_waitcnt vmcnt(0) lgkmcnt(0)
	s_branch .Lp0_entry
